# P3 retention-state scan software-pipelined: chunk loads on running pointers, first 32 issued behind the decay load (log-sigmoid chain runs under them), 16 more issued per 16 processed chunks; counted
# baseline (speedup 1.0000x reference)
; __device__ __forceinline__ float log_sigmoid(float x) { return -log1pf(expf(-x)); }
; __global__ void __launch_bounds__(512, 2) fwd_mega(Args a) {
;     ...
;         if (sb >= 0)
;         for (int idx = sb * 512 + tid; idx < 131072; idx += sG * 512) {
;             const int p = idx & 8191, bh = (idx >> 13) & 7, dir = idx >> 16, h = bh & 3;
;             const float lg = log_sigmoid(dir ? a.in[6][h] : a.in[5][h]); const float dec = expf(lg * 128.f);
;             const size_t base = (size_t)(dir * 8 + bh) * 64 * 16384 + (size_t)p * 2;
;             const bf16* kv = KVC + base; bf16* st = ST + base;
;             float s0 = 0.f, s1 = 0.f;
;             const unsigned* kvw = (const unsigned*)kv; unsigned* stw = (unsigned*)st;
;             for (int c0 = 0; c0 < 64; c0 += 16) {
;                 unsigned w[16];
; #pragma unroll
;                 for (int i = 0; i < 16; ++i) { const int cc = dir ? 63 - (c0 + i) : c0 + i; w[i] = kvw[(size_t)cc * 8192]; }
.LBB0_377:
	v_cmp_gt_u32_e32 vcc, s26, v26
	v_lshrrev_b32_e32 v0, 11, v26
	v_and_b32_e32 v0, 12, v0
	v_cndmask_b32_e32 v3, v27, v28, vcc
	v_cndmask_b32_e32 v2, v29, v30, vcc
	v_lshl_add_u64 v[2:3], v[2:3], 0, v[0:1]
	global_load_dword v0, v[2:3], off
	v_readlane_b32 s0, v255, 26
	v_readlane_b32 s1, v255, 27
	v_readlane_b32 s58, v255, 24
	v_readlane_b32 s59, v255, 25
	v_lshrrev_b32_e32 v18, 13, v26
	v_ashrrev_i32_e32 v19, 13, v26
	v_bfi_b32 v19, -8, v19, v18
	v_ashrrev_i32_e32 v20, 31, v19
	v_mov_b32_e32 v24, v19
	v_mov_b32_e32 v25, v20
	v_lshlrev_b64 v[24:25], 21, v[24:25]
	v_lshlrev_b32_e32 v18, 2, v26
	v_and_or_b32 v24, v18, s40, v24
	v_mov_b32_e32 v22, 0x1f8000
	v_cndmask_b32_e32 v22, v22, v1, vcc
	v_mov_b32_e32 v23, v1
	v_lshl_add_u64 v[24:25], v[24:25], 0, v[22:23]
	v_lshl_add_u64 v[18:19], s[0:1], 0, v[24:25]
	v_lshl_add_u64 v[20:21], s[58:59], 0, v[24:25]
	v_mov_b32_e32 v22, 0xffff8000
	v_mov_b32_e32 v24, 0x8000
	v_cndmask_b32_e32 v22, v22, v24, vcc
	v_mov_b32_e32 v23, -1
	v_cndmask_b32_e32 v23, v23, v1, vcc
	global_load_dword v33, v[18:19], off
	v_lshl_add_u64 v[18:19], v[18:19], 0, v[22:23]
	global_load_dword v34, v[18:19], off
	v_lshl_add_u64 v[18:19], v[18:19], 0, v[22:23]
	global_load_dword v35, v[18:19], off
	v_lshl_add_u64 v[18:19], v[18:19], 0, v[22:23]
	global_load_dword v36, v[18:19], off
	v_lshl_add_u64 v[18:19], v[18:19], 0, v[22:23]
	global_load_dword v37, v[18:19], off
	v_lshl_add_u64 v[18:19], v[18:19], 0, v[22:23]
	global_load_dword v38, v[18:19], off
	v_lshl_add_u64 v[18:19], v[18:19], 0, v[22:23]
	global_load_dword v39, v[18:19], off
	v_lshl_add_u64 v[18:19], v[18:19], 0, v[22:23]
	global_load_dword v40, v[18:19], off
	v_lshl_add_u64 v[18:19], v[18:19], 0, v[22:23]
	global_load_dword v41, v[18:19], off
	v_lshl_add_u64 v[18:19], v[18:19], 0, v[22:23]
	global_load_dword v42, v[18:19], off
	v_lshl_add_u64 v[18:19], v[18:19], 0, v[22:23]
	global_load_dword v43, v[18:19], off
	v_lshl_add_u64 v[18:19], v[18:19], 0, v[22:23]
	global_load_dword v44, v[18:19], off
	v_lshl_add_u64 v[18:19], v[18:19], 0, v[22:23]
	global_load_dword v45, v[18:19], off
	v_lshl_add_u64 v[18:19], v[18:19], 0, v[22:23]
	global_load_dword v46, v[18:19], off
	v_lshl_add_u64 v[18:19], v[18:19], 0, v[22:23]
	global_load_dword v47, v[18:19], off
	v_lshl_add_u64 v[18:19], v[18:19], 0, v[22:23]
	global_load_dword v48, v[18:19], off
	v_lshl_add_u64 v[18:19], v[18:19], 0, v[22:23]
	global_load_dword v49, v[18:19], off
	v_lshl_add_u64 v[18:19], v[18:19], 0, v[22:23]
	global_load_dword v50, v[18:19], off
	v_lshl_add_u64 v[18:19], v[18:19], 0, v[22:23]
	global_load_dword v51, v[18:19], off
	v_lshl_add_u64 v[18:19], v[18:19], 0, v[22:23]
	global_load_dword v52, v[18:19], off
	v_lshl_add_u64 v[18:19], v[18:19], 0, v[22:23]
	global_load_dword v53, v[18:19], off
	v_lshl_add_u64 v[18:19], v[18:19], 0, v[22:23]
	global_load_dword v54, v[18:19], off
	v_lshl_add_u64 v[18:19], v[18:19], 0, v[22:23]
	global_load_dword v55, v[18:19], off
	v_lshl_add_u64 v[18:19], v[18:19], 0, v[22:23]
	global_load_dword v56, v[18:19], off
	v_lshl_add_u64 v[18:19], v[18:19], 0, v[22:23]
	global_load_dword v57, v[18:19], off
	v_lshl_add_u64 v[18:19], v[18:19], 0, v[22:23]
	global_load_dword v58, v[18:19], off
	v_lshl_add_u64 v[18:19], v[18:19], 0, v[22:23]
	global_load_dword v59, v[18:19], off
	v_lshl_add_u64 v[18:19], v[18:19], 0, v[22:23]
	global_load_dword v60, v[18:19], off
	v_lshl_add_u64 v[18:19], v[18:19], 0, v[22:23]
	global_load_dword v61, v[18:19], off
	v_lshl_add_u64 v[18:19], v[18:19], 0, v[22:23]
	global_load_dword v62, v[18:19], off
	v_lshl_add_u64 v[18:19], v[18:19], 0, v[22:23]
	global_load_dword v63, v[18:19], off
	v_lshl_add_u64 v[18:19], v[18:19], 0, v[22:23]
	global_load_dword v64, v[18:19], off
	v_lshl_add_u64 v[18:19], v[18:19], 0, v[22:23]
	v_lshrrev_b32_e32 v3, 13, v26
	v_ashrrev_i32_e32 v4, 13, v26
	v_bfi_b32 v4, -8, v4, v3
	v_lshlrev_b32_e32 v8, 2, v26
	v_readlane_b32 s44, v255, 10
	v_readlane_b32 s58, v255, 24
	v_readlane_b32 s59, v255, 25
	s_mov_b32 s42, 0
	s_mov_b32 s43, 63
	v_mov_b32_e32 v2, v1
	v_readlane_b32 s45, v255, 11
	v_readlane_b32 s46, v255, 12
	v_readlane_b32 s47, v255, 13
	v_readlane_b32 s48, v255, 14
	v_readlane_b32 s49, v255, 15
	v_readlane_b32 s50, v255, 16
	v_readlane_b32 s51, v255, 17
	v_readlane_b32 s52, v255, 18
	v_readlane_b32 s53, v255, 19
	v_readlane_b32 s54, v255, 20
	v_readlane_b32 s55, v255, 21
	v_readlane_b32 s56, v255, 22
	v_readlane_b32 s57, v255, 23
	s_waitcnt vmcnt(32)
; __device__ __forceinline__ unsigned pk2(float lo, float hi) { return pg8::cvt_pk_bf16(lo, hi); }
; __device__ __forceinline__ float bflo(unsigned w) { return __uint_as_float(w << 16); }
; __device__ __forceinline__ float bfhi(unsigned w) { return __uint_as_float(w & 0xffff0000u); }
; __device__ __forceinline__ float log_sigmoid(float x) { return -log1pf(expf(-x)); }
; __global__ void __launch_bounds__(512, 2) fwd_mega(Args a) {
;     ...
;             const float lg = log_sigmoid(dir ? a.in[6][h] : a.in[5][h]); const float dec = expf(lg * 128.f);
;             const size_t base = (size_t)(dir * 8 + bh) * 64 * 16384 + (size_t)p * 2;
;             const bf16* kv = KVC + base; bf16* st = ST + base;
;             float s0 = 0.f, s1 = 0.f;
;             const unsigned* kvw = (const unsigned*)kv; unsigned* stw = (unsigned*)st;
;             for (int c0 = 0; c0 < 64; c0 += 16) {
;                 unsigned w[16];
; #pragma unroll
;                 for (int i = 0; i < 16; ++i) { const int cc = dir ? 63 - (c0 + i) : c0 + i; w[i] = kvw[(size_t)cc * 8192]; }
; #pragma unroll
;                 for (int i = 0; i < 16; ++i) { const int cc = dir ? 63 - (c0 + i) : c0 + i; stw[(size_t)cc * 8192] = pk2(s0, s1); s0 = fmaf(dec, s0, bflo(w[i])); s1 = fmaf(dec, s1, bfhi(w[i])); }
	v_mul_f32_e32 v5, 0xbfb8aa3b, v0
	v_fma_f32 v6, v0, s27, -v5
	v_rndne_f32_e32 v7, v5
	v_fmac_f32_e32 v6, 0xb2a5705f, v0
	v_sub_f32_e32 v5, v5, v7
	v_add_f32_e32 v5, v5, v6
	v_cvt_i32_f32_e32 v9, v7
	v_exp_f32_e32 v10, v5
	v_cmp_nlt_f32_e64 s[0:1], s28, v0
	v_ashrrev_i32_e32 v5, 31, v4
	v_lshlrev_b64 v[6:7], 21, v[4:5]
	v_ldexp_f32 v3, v10, v9
	v_cndmask_b32_e64 v3, 0, v3, s[0:1]
	v_cmp_ngt_f32_e64 s[0:1], s29, v0
	v_and_or_b32 v6, v8, s40, v6
	s_nop 0
	v_cndmask_b32_e64 v0, v31, v3, s[0:1]
	v_add_f32_e32 v3, 1.0, v0
	v_add_f32_e32 v9, -1.0, v3
	v_frexp_mant_f32_e32 v10, v3
	v_cvt_f64_f32_e32 v[4:5], v3
	v_sub_f32_e32 v11, v9, v3
	v_frexp_exp_i32_f64_e32 v4, v[4:5]
	v_cmp_gt_f32_e64 s[0:1], s31, v10
	v_sub_f32_e32 v9, v0, v9
	v_add_f32_e32 v5, 1.0, v11
	v_subbrev_co_u32_e64 v4, s[0:1], 0, v4, s[0:1]
	v_add_f32_e32 v5, v9, v5
	v_sub_u32_e32 v9, 0, v4
	v_cvt_f32_i32_e32 v4, v4
	v_ldexp_f32 v3, v3, v9
	v_ldexp_f32 v5, v5, v9
	v_add_f32_e32 v9, -1.0, v3
	v_add_f32_e32 v10, 1.0, v3
	v_add_f32_e32 v11, 1.0, v9
	v_add_f32_e32 v12, -1.0, v10
	v_sub_f32_e32 v11, v3, v11
	v_sub_f32_e32 v3, v3, v12
	v_mul_f32_e32 v12, 0x3f317218, v4
	v_add_f32_e32 v11, v5, v11
	v_add_f32_e32 v3, v5, v3
	v_fma_f32 v5, v4, s33, -v12
	v_add_f32_e32 v13, v9, v11
	v_add_f32_e32 v14, v10, v3
	v_fmac_f32_e32 v5, 0xb102e308, v4
	v_sub_f32_e32 v4, v9, v13
	v_sub_f32_e32 v9, v10, v14
	v_rcp_f32_e32 v10, v14
	v_add_f32_e32 v15, v12, v5
	v_add_f32_e32 v3, v3, v9
	v_sub_f32_e32 v9, v15, v12
	v_sub_f32_e32 v5, v5, v9
	v_mul_f32_e32 v9, v13, v10
	v_add_f32_e32 v4, v11, v4
	v_mul_f32_e32 v11, v14, v9
	v_fma_f32 v12, v9, v14, -v11
	v_fmac_f32_e32 v12, v9, v3
	v_add_f32_e32 v16, v11, v12
	v_sub_f32_e32 v17, v13, v16
	v_sub_f32_e32 v11, v16, v11
	v_sub_f32_e32 v13, v13, v17
	v_sub_f32_e32 v11, v11, v12
	v_sub_f32_e32 v12, v13, v16
	v_add_f32_e32 v4, v4, v12
	v_add_f32_e32 v4, v11, v4
	v_add_f32_e32 v11, v17, v4
	v_mul_f32_e32 v12, v10, v11
	v_sub_f32_e32 v13, v17, v11
	v_mul_f32_e32 v16, v14, v12
	v_add_f32_e32 v4, v4, v13
	v_add_f32_e32 v13, v9, v12
	v_fma_f32 v14, v12, v14, -v16
	v_sub_f32_e32 v9, v13, v9
	v_fmac_f32_e32 v14, v12, v3
	v_sub_f32_e32 v3, v12, v9
	v_add_f32_e32 v9, v16, v14
	v_sub_f32_e32 v12, v9, v16
	v_sub_f32_e32 v16, v11, v9
	v_sub_f32_e32 v11, v11, v16
	v_sub_f32_e32 v9, v11, v9
	v_sub_f32_e32 v12, v12, v14
	v_add_f32_e32 v4, v4, v9
	v_add_f32_e32 v4, v12, v4
	v_add_f32_e32 v4, v16, v4
	v_mul_f32_e32 v4, v10, v4
	v_add_f32_e32 v3, v3, v4
	v_add_f32_e32 v4, v13, v3
	v_mul_f32_e32 v9, v4, v4
	v_fmamk_f32 v12, v9, 0x3e9b6dac, v32
	v_sub_f32_e32 v10, v4, v13
	v_ldexp_f32 v11, v4, 1
	v_mul_f32_e32 v4, v4, v9
	v_fmaak_f32 v9, v9, v12, 0x3f2aaada
	v_mul_f32_e32 v4, v4, v9
	v_add_f32_e32 v9, v11, v4
	v_sub_f32_e32 v3, v3, v10
	v_sub_f32_e32 v10, v9, v11
	v_ldexp_f32 v3, v3, 1
	v_sub_f32_e32 v4, v4, v10
	v_add_f32_e32 v3, v3, v4
	v_add_f32_e32 v4, v9, v3
	v_sub_f32_e32 v9, v4, v9
	v_add_f32_e32 v10, v15, v4
	v_sub_f32_e32 v3, v3, v9
	v_sub_f32_e32 v9, v10, v15
	v_sub_f32_e32 v11, v10, v9
	v_sub_f32_e32 v4, v4, v9
	v_add_f32_e32 v9, v5, v3
	v_sub_f32_e32 v11, v15, v11
	v_sub_f32_e32 v12, v9, v5
	v_add_f32_e32 v4, v4, v11
	v_sub_f32_e32 v11, v9, v12
	v_sub_f32_e32 v3, v3, v12
	v_sub_f32_e32 v5, v5, v11
	v_add_f32_e32 v4, v9, v4
	v_add_f32_e32 v3, v3, v5
	v_add_f32_e32 v5, v10, v4
	v_sub_f32_e32 v9, v5, v10
	v_sub_f32_e32 v4, v4, v9
	v_add_f32_e32 v3, v3, v4
	v_add_f32_e32 v3, v5, v3
	v_cmp_neq_f32_e64 s[0:1], s30, v0
	s_nop 1
	v_cndmask_b32_e64 v3, v31, v3, s[0:1]
	v_cmp_lt_f32_e64 s[0:1], |v0|, s34
	s_nop 1
	v_cndmask_b32_e64 v0, v3, v0, s[0:1]
	v_mul_f32_e32 v0, 0xc3000000, v0
	v_mul_f32_e32 v3, 0x3fb8aa3b, v0
	v_fma_f32 v4, v0, s35, -v3
	v_rndne_f32_e32 v5, v3
	v_fmac_f32_e32 v4, 0x32a5705f, v0
	v_sub_f32_e32 v3, v3, v5
	v_add_f32_e32 v3, v3, v4
	v_cvt_i32_f32_e32 v9, v5
	v_exp_f32_e32 v3, v3
	v_readlane_b32 s0, v255, 26
	v_readlane_b32 s1, v255, 27
	v_ldexp_f32 v3, v3, v9
	s_nop 0
	v_lshl_add_u64 v[4:5], s[0:1], 0, v[6:7]
	v_cmp_ngt_f32_e64 s[0:1], s38, v0
	v_lshl_add_u64 v[6:7], s[58:59], 0, v[6:7]
	s_nop 0
	v_cndmask_b32_e64 v3, 0, v3, s[0:1]
	v_cmp_nlt_f32_e64 s[0:1], s39, v0
	s_nop 1
	v_cndmask_b32_e64 v8, v31, v3, s[0:1]
	v_mov_b32_e32 v9, v8
	v_mov_b32_e32 v3, v1
	v_cvt_pk_bf16_f32 v65, v2, v3
	global_store_dword v[20:21], v65, off
	v_lshl_add_u64 v[20:21], v[20:21], 0, v[22:23]
	s_waitcnt vmcnt(32)
	v_lshlrev_b32_e32 v24, 16, v33
	v_and_b32_e32 v25, 0xffff0000, v33
	v_pk_fma_f32 v[2:3], v[8:9], v[2:3], v[24:25]
	v_cvt_pk_bf16_f32 v65, v2, v3
	global_store_dword v[20:21], v65, off
	v_lshl_add_u64 v[20:21], v[20:21], 0, v[22:23]
	s_waitcnt vmcnt(32)
	v_lshlrev_b32_e32 v24, 16, v34
	v_and_b32_e32 v25, 0xffff0000, v34
	v_pk_fma_f32 v[2:3], v[8:9], v[2:3], v[24:25]
	v_cvt_pk_bf16_f32 v65, v2, v3
	global_store_dword v[20:21], v65, off
	v_lshl_add_u64 v[20:21], v[20:21], 0, v[22:23]
	s_waitcnt vmcnt(32)
	v_lshlrev_b32_e32 v24, 16, v35
	v_and_b32_e32 v25, 0xffff0000, v35
	v_pk_fma_f32 v[2:3], v[8:9], v[2:3], v[24:25]
	v_cvt_pk_bf16_f32 v65, v2, v3
	global_store_dword v[20:21], v65, off
	v_lshl_add_u64 v[20:21], v[20:21], 0, v[22:23]
	s_waitcnt vmcnt(32)
	v_lshlrev_b32_e32 v24, 16, v36
	v_and_b32_e32 v25, 0xffff0000, v36
	v_pk_fma_f32 v[2:3], v[8:9], v[2:3], v[24:25]
	v_cvt_pk_bf16_f32 v65, v2, v3
	global_store_dword v[20:21], v65, off
	v_lshl_add_u64 v[20:21], v[20:21], 0, v[22:23]
	s_waitcnt vmcnt(32)
	v_lshlrev_b32_e32 v24, 16, v37
	v_and_b32_e32 v25, 0xffff0000, v37
	v_pk_fma_f32 v[2:3], v[8:9], v[2:3], v[24:25]
	v_cvt_pk_bf16_f32 v65, v2, v3
	global_store_dword v[20:21], v65, off
	v_lshl_add_u64 v[20:21], v[20:21], 0, v[22:23]
	s_waitcnt vmcnt(32)
; __device__ __forceinline__ unsigned pk2(float lo, float hi) { return pg8::cvt_pk_bf16(lo, hi); }
; __device__ __forceinline__ float bflo(unsigned w) { return __uint_as_float(w << 16); }
; __device__ __forceinline__ float bfhi(unsigned w) { return __uint_as_float(w & 0xffff0000u); }
; __global__ void __launch_bounds__(512, 2) fwd_mega(Args a) {
;     ...
;             for (int c0 = 0; c0 < 64; c0 += 16) {
;                 unsigned w[16];
; #pragma unroll
;                 for (int i = 0; i < 16; ++i) { const int cc = dir ? 63 - (c0 + i) : c0 + i; w[i] = kvw[(size_t)cc * 8192]; }
; #pragma unroll
;                 for (int i = 0; i < 16; ++i) { const int cc = dir ? 63 - (c0 + i) : c0 + i; stw[(size_t)cc * 8192] = pk2(s0, s1); s0 = fmaf(dec, s0, bflo(w[i])); s1 = fmaf(dec, s1, bfhi(w[i])); }
	v_lshlrev_b32_e32 v24, 16, v38
	v_and_b32_e32 v25, 0xffff0000, v38
	v_pk_fma_f32 v[2:3], v[8:9], v[2:3], v[24:25]
	v_cvt_pk_bf16_f32 v65, v2, v3
	global_store_dword v[20:21], v65, off
	v_lshl_add_u64 v[20:21], v[20:21], 0, v[22:23]
	s_waitcnt vmcnt(32)
	v_lshlrev_b32_e32 v24, 16, v39
	v_and_b32_e32 v25, 0xffff0000, v39
	v_pk_fma_f32 v[2:3], v[8:9], v[2:3], v[24:25]
	v_cvt_pk_bf16_f32 v65, v2, v3
	global_store_dword v[20:21], v65, off
	v_lshl_add_u64 v[20:21], v[20:21], 0, v[22:23]
	s_waitcnt vmcnt(32)
	v_lshlrev_b32_e32 v24, 16, v40
	v_and_b32_e32 v25, 0xffff0000, v40
	v_pk_fma_f32 v[2:3], v[8:9], v[2:3], v[24:25]
	v_cvt_pk_bf16_f32 v65, v2, v3
	global_store_dword v[20:21], v65, off
	v_lshl_add_u64 v[20:21], v[20:21], 0, v[22:23]
	s_waitcnt vmcnt(32)
	v_lshlrev_b32_e32 v24, 16, v41
	v_and_b32_e32 v25, 0xffff0000, v41
	v_pk_fma_f32 v[2:3], v[8:9], v[2:3], v[24:25]
	v_cvt_pk_bf16_f32 v65, v2, v3
	global_store_dword v[20:21], v65, off
	v_lshl_add_u64 v[20:21], v[20:21], 0, v[22:23]
	s_waitcnt vmcnt(32)
	v_lshlrev_b32_e32 v24, 16, v42
	v_and_b32_e32 v25, 0xffff0000, v42
	v_pk_fma_f32 v[2:3], v[8:9], v[2:3], v[24:25]
	v_cvt_pk_bf16_f32 v65, v2, v3
	global_store_dword v[20:21], v65, off
	v_lshl_add_u64 v[20:21], v[20:21], 0, v[22:23]
	s_waitcnt vmcnt(32)
	v_lshlrev_b32_e32 v24, 16, v43
	v_and_b32_e32 v25, 0xffff0000, v43
	v_pk_fma_f32 v[2:3], v[8:9], v[2:3], v[24:25]
	v_cvt_pk_bf16_f32 v65, v2, v3
	global_store_dword v[20:21], v65, off
	v_lshl_add_u64 v[20:21], v[20:21], 0, v[22:23]
	s_waitcnt vmcnt(32)
	v_lshlrev_b32_e32 v24, 16, v44
	v_and_b32_e32 v25, 0xffff0000, v44
	v_pk_fma_f32 v[2:3], v[8:9], v[2:3], v[24:25]
	v_cvt_pk_bf16_f32 v65, v2, v3
	global_store_dword v[20:21], v65, off
	v_lshl_add_u64 v[20:21], v[20:21], 0, v[22:23]
	s_waitcnt vmcnt(32)
	v_lshlrev_b32_e32 v24, 16, v45
	v_and_b32_e32 v25, 0xffff0000, v45
	v_pk_fma_f32 v[2:3], v[8:9], v[2:3], v[24:25]
	v_cvt_pk_bf16_f32 v65, v2, v3
	global_store_dword v[20:21], v65, off
	v_lshl_add_u64 v[20:21], v[20:21], 0, v[22:23]
	s_waitcnt vmcnt(32)
	v_lshlrev_b32_e32 v24, 16, v46
	v_and_b32_e32 v25, 0xffff0000, v46
	v_pk_fma_f32 v[2:3], v[8:9], v[2:3], v[24:25]
	v_cvt_pk_bf16_f32 v65, v2, v3
	global_store_dword v[20:21], v65, off
	v_lshl_add_u64 v[20:21], v[20:21], 0, v[22:23]
	s_waitcnt vmcnt(32)
	v_lshlrev_b32_e32 v24, 16, v47
	v_and_b32_e32 v25, 0xffff0000, v47
	v_pk_fma_f32 v[2:3], v[8:9], v[2:3], v[24:25]
	v_cvt_pk_bf16_f32 v65, v2, v3
	global_store_dword v[20:21], v65, off
	v_lshl_add_u64 v[20:21], v[20:21], 0, v[22:23]
	s_waitcnt vmcnt(32)
	v_lshlrev_b32_e32 v24, 16, v48
	v_and_b32_e32 v25, 0xffff0000, v48
	v_pk_fma_f32 v[2:3], v[8:9], v[2:3], v[24:25]
	global_load_dword v33, v[18:19], off
	v_lshl_add_u64 v[18:19], v[18:19], 0, v[22:23]
	global_load_dword v34, v[18:19], off
	v_lshl_add_u64 v[18:19], v[18:19], 0, v[22:23]
	global_load_dword v35, v[18:19], off
	v_lshl_add_u64 v[18:19], v[18:19], 0, v[22:23]
	global_load_dword v36, v[18:19], off
	v_lshl_add_u64 v[18:19], v[18:19], 0, v[22:23]
	global_load_dword v37, v[18:19], off
	v_lshl_add_u64 v[18:19], v[18:19], 0, v[22:23]
	global_load_dword v38, v[18:19], off
	v_lshl_add_u64 v[18:19], v[18:19], 0, v[22:23]
	global_load_dword v39, v[18:19], off
	v_lshl_add_u64 v[18:19], v[18:19], 0, v[22:23]
	global_load_dword v40, v[18:19], off
	v_lshl_add_u64 v[18:19], v[18:19], 0, v[22:23]
	global_load_dword v41, v[18:19], off
	v_lshl_add_u64 v[18:19], v[18:19], 0, v[22:23]
	global_load_dword v42, v[18:19], off
	v_lshl_add_u64 v[18:19], v[18:19], 0, v[22:23]
	global_load_dword v43, v[18:19], off
	v_lshl_add_u64 v[18:19], v[18:19], 0, v[22:23]
	global_load_dword v44, v[18:19], off
	v_lshl_add_u64 v[18:19], v[18:19], 0, v[22:23]
	global_load_dword v45, v[18:19], off
	v_lshl_add_u64 v[18:19], v[18:19], 0, v[22:23]
	global_load_dword v46, v[18:19], off
	v_lshl_add_u64 v[18:19], v[18:19], 0, v[22:23]
	global_load_dword v47, v[18:19], off
	v_lshl_add_u64 v[18:19], v[18:19], 0, v[22:23]
	global_load_dword v48, v[18:19], off
	v_lshl_add_u64 v[18:19], v[18:19], 0, v[22:23]
	v_cvt_pk_bf16_f32 v65, v2, v3
	global_store_dword v[20:21], v65, off
	v_lshl_add_u64 v[20:21], v[20:21], 0, v[22:23]
	s_waitcnt vmcnt(48)
	v_lshlrev_b32_e32 v24, 16, v49
	v_and_b32_e32 v25, 0xffff0000, v49
	v_pk_fma_f32 v[2:3], v[8:9], v[2:3], v[24:25]
	v_cvt_pk_bf16_f32 v65, v2, v3
	global_store_dword v[20:21], v65, off
	v_lshl_add_u64 v[20:21], v[20:21], 0, v[22:23]
	s_waitcnt vmcnt(48)
	v_lshlrev_b32_e32 v24, 16, v50
	v_and_b32_e32 v25, 0xffff0000, v50
	v_pk_fma_f32 v[2:3], v[8:9], v[2:3], v[24:25]
	v_cvt_pk_bf16_f32 v65, v2, v3
	global_store_dword v[20:21], v65, off
	v_lshl_add_u64 v[20:21], v[20:21], 0, v[22:23]
	s_waitcnt vmcnt(48)
	v_lshlrev_b32_e32 v24, 16, v51
	v_and_b32_e32 v25, 0xffff0000, v51
	v_pk_fma_f32 v[2:3], v[8:9], v[2:3], v[24:25]
	v_cvt_pk_bf16_f32 v65, v2, v3
	global_store_dword v[20:21], v65, off
	v_lshl_add_u64 v[20:21], v[20:21], 0, v[22:23]
	s_waitcnt vmcnt(48)
	v_lshlrev_b32_e32 v24, 16, v52
	v_and_b32_e32 v25, 0xffff0000, v52
	v_pk_fma_f32 v[2:3], v[8:9], v[2:3], v[24:25]
	v_cvt_pk_bf16_f32 v65, v2, v3
	global_store_dword v[20:21], v65, off
	v_lshl_add_u64 v[20:21], v[20:21], 0, v[22:23]
	s_waitcnt vmcnt(48)
	v_lshlrev_b32_e32 v24, 16, v53
	v_and_b32_e32 v25, 0xffff0000, v53
	v_pk_fma_f32 v[2:3], v[8:9], v[2:3], v[24:25]
	v_cvt_pk_bf16_f32 v65, v2, v3
	global_store_dword v[20:21], v65, off
	v_lshl_add_u64 v[20:21], v[20:21], 0, v[22:23]
	s_waitcnt vmcnt(48)
	v_lshlrev_b32_e32 v24, 16, v54
	v_and_b32_e32 v25, 0xffff0000, v54
	v_pk_fma_f32 v[2:3], v[8:9], v[2:3], v[24:25]
	v_cvt_pk_bf16_f32 v65, v2, v3
	global_store_dword v[20:21], v65, off
	v_lshl_add_u64 v[20:21], v[20:21], 0, v[22:23]
	s_waitcnt vmcnt(48)
; __device__ __forceinline__ unsigned pk2(float lo, float hi) { return pg8::cvt_pk_bf16(lo, hi); }
; __device__ __forceinline__ float bflo(unsigned w) { return __uint_as_float(w << 16); }
; __device__ __forceinline__ float bfhi(unsigned w) { return __uint_as_float(w & 0xffff0000u); }
; __global__ void __launch_bounds__(512, 2) fwd_mega(Args a) {
;     ...
;             for (int c0 = 0; c0 < 64; c0 += 16) {
;                 unsigned w[16];
; #pragma unroll
;                 for (int i = 0; i < 16; ++i) { const int cc = dir ? 63 - (c0 + i) : c0 + i; w[i] = kvw[(size_t)cc * 8192]; }
; #pragma unroll
;                 for (int i = 0; i < 16; ++i) { const int cc = dir ? 63 - (c0 + i) : c0 + i; stw[(size_t)cc * 8192] = pk2(s0, s1); s0 = fmaf(dec, s0, bflo(w[i])); s1 = fmaf(dec, s1, bfhi(w[i])); }
	v_lshlrev_b32_e32 v24, 16, v55
	v_and_b32_e32 v25, 0xffff0000, v55
	v_pk_fma_f32 v[2:3], v[8:9], v[2:3], v[24:25]
	v_cvt_pk_bf16_f32 v65, v2, v3
	global_store_dword v[20:21], v65, off
	v_lshl_add_u64 v[20:21], v[20:21], 0, v[22:23]
	s_waitcnt vmcnt(48)
	v_lshlrev_b32_e32 v24, 16, v56
	v_and_b32_e32 v25, 0xffff0000, v56
	v_pk_fma_f32 v[2:3], v[8:9], v[2:3], v[24:25]
	v_cvt_pk_bf16_f32 v65, v2, v3
	global_store_dword v[20:21], v65, off
	v_lshl_add_u64 v[20:21], v[20:21], 0, v[22:23]
	s_waitcnt vmcnt(48)
	v_lshlrev_b32_e32 v24, 16, v57
	v_and_b32_e32 v25, 0xffff0000, v57
	v_pk_fma_f32 v[2:3], v[8:9], v[2:3], v[24:25]
	v_cvt_pk_bf16_f32 v65, v2, v3
	global_store_dword v[20:21], v65, off
	v_lshl_add_u64 v[20:21], v[20:21], 0, v[22:23]
	s_waitcnt vmcnt(48)
	v_lshlrev_b32_e32 v24, 16, v58
	v_and_b32_e32 v25, 0xffff0000, v58
	v_pk_fma_f32 v[2:3], v[8:9], v[2:3], v[24:25]
	v_cvt_pk_bf16_f32 v65, v2, v3
	global_store_dword v[20:21], v65, off
	v_lshl_add_u64 v[20:21], v[20:21], 0, v[22:23]
	s_waitcnt vmcnt(48)
	v_lshlrev_b32_e32 v24, 16, v59
	v_and_b32_e32 v25, 0xffff0000, v59
	v_pk_fma_f32 v[2:3], v[8:9], v[2:3], v[24:25]
	v_cvt_pk_bf16_f32 v65, v2, v3
	global_store_dword v[20:21], v65, off
	v_lshl_add_u64 v[20:21], v[20:21], 0, v[22:23]
	s_waitcnt vmcnt(48)
	v_lshlrev_b32_e32 v24, 16, v60
	v_and_b32_e32 v25, 0xffff0000, v60
	v_pk_fma_f32 v[2:3], v[8:9], v[2:3], v[24:25]
	v_cvt_pk_bf16_f32 v65, v2, v3
	global_store_dword v[20:21], v65, off
	v_lshl_add_u64 v[20:21], v[20:21], 0, v[22:23]
	s_waitcnt vmcnt(48)
	v_lshlrev_b32_e32 v24, 16, v61
	v_and_b32_e32 v25, 0xffff0000, v61
	v_pk_fma_f32 v[2:3], v[8:9], v[2:3], v[24:25]
	v_cvt_pk_bf16_f32 v65, v2, v3
	global_store_dword v[20:21], v65, off
	v_lshl_add_u64 v[20:21], v[20:21], 0, v[22:23]
	s_waitcnt vmcnt(48)
	v_lshlrev_b32_e32 v24, 16, v62
	v_and_b32_e32 v25, 0xffff0000, v62
	v_pk_fma_f32 v[2:3], v[8:9], v[2:3], v[24:25]
	v_cvt_pk_bf16_f32 v65, v2, v3
	global_store_dword v[20:21], v65, off
	v_lshl_add_u64 v[20:21], v[20:21], 0, v[22:23]
	s_waitcnt vmcnt(48)
	v_lshlrev_b32_e32 v24, 16, v63
	v_and_b32_e32 v25, 0xffff0000, v63
	v_pk_fma_f32 v[2:3], v[8:9], v[2:3], v[24:25]
	v_cvt_pk_bf16_f32 v65, v2, v3
	global_store_dword v[20:21], v65, off
	v_lshl_add_u64 v[20:21], v[20:21], 0, v[22:23]
	s_waitcnt vmcnt(48)
	v_lshlrev_b32_e32 v24, 16, v64
	v_and_b32_e32 v25, 0xffff0000, v64
	v_pk_fma_f32 v[2:3], v[8:9], v[2:3], v[24:25]
	global_load_dword v49, v[18:19], off
	v_lshl_add_u64 v[18:19], v[18:19], 0, v[22:23]
	global_load_dword v50, v[18:19], off
	v_lshl_add_u64 v[18:19], v[18:19], 0, v[22:23]
	global_load_dword v51, v[18:19], off
	v_lshl_add_u64 v[18:19], v[18:19], 0, v[22:23]
	global_load_dword v52, v[18:19], off
	v_lshl_add_u64 v[18:19], v[18:19], 0, v[22:23]
	global_load_dword v53, v[18:19], off
	v_lshl_add_u64 v[18:19], v[18:19], 0, v[22:23]
	global_load_dword v54, v[18:19], off
	v_lshl_add_u64 v[18:19], v[18:19], 0, v[22:23]
	global_load_dword v55, v[18:19], off
	v_lshl_add_u64 v[18:19], v[18:19], 0, v[22:23]
	global_load_dword v56, v[18:19], off
	v_lshl_add_u64 v[18:19], v[18:19], 0, v[22:23]
	global_load_dword v57, v[18:19], off
	v_lshl_add_u64 v[18:19], v[18:19], 0, v[22:23]
	global_load_dword v58, v[18:19], off
	v_lshl_add_u64 v[18:19], v[18:19], 0, v[22:23]
	global_load_dword v59, v[18:19], off
	v_lshl_add_u64 v[18:19], v[18:19], 0, v[22:23]
	global_load_dword v60, v[18:19], off
	v_lshl_add_u64 v[18:19], v[18:19], 0, v[22:23]
	global_load_dword v61, v[18:19], off
	v_lshl_add_u64 v[18:19], v[18:19], 0, v[22:23]
	global_load_dword v62, v[18:19], off
	v_lshl_add_u64 v[18:19], v[18:19], 0, v[22:23]
	global_load_dword v63, v[18:19], off
	v_lshl_add_u64 v[18:19], v[18:19], 0, v[22:23]
	global_load_dword v64, v[18:19], off
	v_lshl_add_u64 v[18:19], v[18:19], 0, v[22:23]
	v_cvt_pk_bf16_f32 v65, v2, v3
	global_store_dword v[20:21], v65, off
	v_lshl_add_u64 v[20:21], v[20:21], 0, v[22:23]
	s_waitcnt vmcnt(48)
	v_lshlrev_b32_e32 v24, 16, v33
	v_and_b32_e32 v25, 0xffff0000, v33
	v_pk_fma_f32 v[2:3], v[8:9], v[2:3], v[24:25]
	v_cvt_pk_bf16_f32 v65, v2, v3
	global_store_dword v[20:21], v65, off
	v_lshl_add_u64 v[20:21], v[20:21], 0, v[22:23]
	s_waitcnt vmcnt(48)
	v_lshlrev_b32_e32 v24, 16, v34
	v_and_b32_e32 v25, 0xffff0000, v34
	v_pk_fma_f32 v[2:3], v[8:9], v[2:3], v[24:25]
	v_cvt_pk_bf16_f32 v65, v2, v3
	global_store_dword v[20:21], v65, off
	v_lshl_add_u64 v[20:21], v[20:21], 0, v[22:23]
	s_waitcnt vmcnt(48)
	v_lshlrev_b32_e32 v24, 16, v35
	v_and_b32_e32 v25, 0xffff0000, v35
	v_pk_fma_f32 v[2:3], v[8:9], v[2:3], v[24:25]
	v_cvt_pk_bf16_f32 v65, v2, v3
	global_store_dword v[20:21], v65, off
	v_lshl_add_u64 v[20:21], v[20:21], 0, v[22:23]
	s_waitcnt vmcnt(48)
	v_lshlrev_b32_e32 v24, 16, v36
	v_and_b32_e32 v25, 0xffff0000, v36
	v_pk_fma_f32 v[2:3], v[8:9], v[2:3], v[24:25]
	v_cvt_pk_bf16_f32 v65, v2, v3
	global_store_dword v[20:21], v65, off
	v_lshl_add_u64 v[20:21], v[20:21], 0, v[22:23]
	s_waitcnt vmcnt(48)
	v_lshlrev_b32_e32 v24, 16, v37
	v_and_b32_e32 v25, 0xffff0000, v37
	v_pk_fma_f32 v[2:3], v[8:9], v[2:3], v[24:25]
	v_cvt_pk_bf16_f32 v65, v2, v3
	global_store_dword v[20:21], v65, off
	v_lshl_add_u64 v[20:21], v[20:21], 0, v[22:23]
	s_waitcnt vmcnt(48)
	v_lshlrev_b32_e32 v24, 16, v38
	v_and_b32_e32 v25, 0xffff0000, v38
	v_pk_fma_f32 v[2:3], v[8:9], v[2:3], v[24:25]
	v_cvt_pk_bf16_f32 v65, v2, v3
	global_store_dword v[20:21], v65, off
	v_lshl_add_u64 v[20:21], v[20:21], 0, v[22:23]
	s_waitcnt vmcnt(48)
	v_lshlrev_b32_e32 v24, 16, v39
	v_and_b32_e32 v25, 0xffff0000, v39
	v_pk_fma_f32 v[2:3], v[8:9], v[2:3], v[24:25]
	v_cvt_pk_bf16_f32 v65, v2, v3
	global_store_dword v[20:21], v65, off
	v_lshl_add_u64 v[20:21], v[20:21], 0, v[22:23]
	s_waitcnt vmcnt(48)
; __device__ __forceinline__ unsigned pk2(float lo, float hi) { return pg8::cvt_pk_bf16(lo, hi); }
; __device__ __forceinline__ float bflo(unsigned w) { return __uint_as_float(w << 16); }
; __device__ __forceinline__ float bfhi(unsigned w) { return __uint_as_float(w & 0xffff0000u); }
; __device__ __forceinline__ float log_sigmoid(float x) { return -log1pf(expf(-x)); }
; __global__ void __launch_bounds__(512, 2) fwd_mega(Args a) {
;     ...
;         for (int idx = sb * 512 + tid; idx < 131072; idx += sG * 512) {
;             const int p = idx & 8191, bh = (idx >> 13) & 7, dir = idx >> 16, h = bh & 3;
;             const float lg = log_sigmoid(dir ? a.in[6][h] : a.in[5][h]); const float dec = expf(lg * 128.f);
;             const size_t base = (size_t)(dir * 8 + bh) * 64 * 16384 + (size_t)p * 2;
;             const bf16* kv = KVC + base; bf16* st = ST + base;
;             float s0 = 0.f, s1 = 0.f;
;             const unsigned* kvw = (const unsigned*)kv; unsigned* stw = (unsigned*)st;
;             for (int c0 = 0; c0 < 64; c0 += 16) {
;                 unsigned w[16];
; #pragma unroll
;                 for (int i = 0; i < 16; ++i) { const int cc = dir ? 63 - (c0 + i) : c0 + i; w[i] = kvw[(size_t)cc * 8192]; }
; #pragma unroll
;                 for (int i = 0; i < 16; ++i) { const int cc = dir ? 63 - (c0 + i) : c0 + i; stw[(size_t)cc * 8192] = pk2(s0, s1); s0 = fmaf(dec, s0, bflo(w[i])); s1 = fmaf(dec, s1, bfhi(w[i])); }
	v_lshlrev_b32_e32 v24, 16, v40
	v_and_b32_e32 v25, 0xffff0000, v40
	v_pk_fma_f32 v[2:3], v[8:9], v[2:3], v[24:25]
	v_cvt_pk_bf16_f32 v65, v2, v3
	global_store_dword v[20:21], v65, off
	v_lshl_add_u64 v[20:21], v[20:21], 0, v[22:23]
	s_waitcnt vmcnt(48)
	v_lshlrev_b32_e32 v24, 16, v41
	v_and_b32_e32 v25, 0xffff0000, v41
	v_pk_fma_f32 v[2:3], v[8:9], v[2:3], v[24:25]
	v_cvt_pk_bf16_f32 v65, v2, v3
	global_store_dword v[20:21], v65, off
	v_lshl_add_u64 v[20:21], v[20:21], 0, v[22:23]
	s_waitcnt vmcnt(48)
	v_lshlrev_b32_e32 v24, 16, v42
	v_and_b32_e32 v25, 0xffff0000, v42
	v_pk_fma_f32 v[2:3], v[8:9], v[2:3], v[24:25]
	v_cvt_pk_bf16_f32 v65, v2, v3
	global_store_dword v[20:21], v65, off
	v_lshl_add_u64 v[20:21], v[20:21], 0, v[22:23]
	s_waitcnt vmcnt(48)
	v_lshlrev_b32_e32 v24, 16, v43
	v_and_b32_e32 v25, 0xffff0000, v43
	v_pk_fma_f32 v[2:3], v[8:9], v[2:3], v[24:25]
	v_cvt_pk_bf16_f32 v65, v2, v3
	global_store_dword v[20:21], v65, off
	v_lshl_add_u64 v[20:21], v[20:21], 0, v[22:23]
	s_waitcnt vmcnt(48)
	v_lshlrev_b32_e32 v24, 16, v44
	v_and_b32_e32 v25, 0xffff0000, v44
	v_pk_fma_f32 v[2:3], v[8:9], v[2:3], v[24:25]
	v_cvt_pk_bf16_f32 v65, v2, v3
	global_store_dword v[20:21], v65, off
	v_lshl_add_u64 v[20:21], v[20:21], 0, v[22:23]
	s_waitcnt vmcnt(48)
	v_lshlrev_b32_e32 v24, 16, v45
	v_and_b32_e32 v25, 0xffff0000, v45
	v_pk_fma_f32 v[2:3], v[8:9], v[2:3], v[24:25]
	v_cvt_pk_bf16_f32 v65, v2, v3
	global_store_dword v[20:21], v65, off
	v_lshl_add_u64 v[20:21], v[20:21], 0, v[22:23]
	s_waitcnt vmcnt(48)
	v_lshlrev_b32_e32 v24, 16, v46
	v_and_b32_e32 v25, 0xffff0000, v46
	v_pk_fma_f32 v[2:3], v[8:9], v[2:3], v[24:25]
	v_cvt_pk_bf16_f32 v65, v2, v3
	global_store_dword v[20:21], v65, off
	v_lshl_add_u64 v[20:21], v[20:21], 0, v[22:23]
	s_waitcnt vmcnt(48)
	v_lshlrev_b32_e32 v24, 16, v47
	v_and_b32_e32 v25, 0xffff0000, v47
	v_pk_fma_f32 v[2:3], v[8:9], v[2:3], v[24:25]
	v_cvt_pk_bf16_f32 v65, v2, v3
	global_store_dword v[20:21], v65, off
	v_lshl_add_u64 v[20:21], v[20:21], 0, v[22:23]
	s_waitcnt vmcnt(48)
	v_lshlrev_b32_e32 v24, 16, v48
	v_and_b32_e32 v25, 0xffff0000, v48
	v_pk_fma_f32 v[2:3], v[8:9], v[2:3], v[24:25]
	v_cvt_pk_bf16_f32 v65, v2, v3
	global_store_dword v[20:21], v65, off
	v_lshl_add_u64 v[20:21], v[20:21], 0, v[22:23]
	s_waitcnt vmcnt(32)
	v_lshlrev_b32_e32 v24, 16, v49
	v_and_b32_e32 v25, 0xffff0000, v49
	v_pk_fma_f32 v[2:3], v[8:9], v[2:3], v[24:25]
	v_cvt_pk_bf16_f32 v65, v2, v3
	global_store_dword v[20:21], v65, off
	v_lshl_add_u64 v[20:21], v[20:21], 0, v[22:23]
	s_waitcnt vmcnt(32)
	v_lshlrev_b32_e32 v24, 16, v50
	v_and_b32_e32 v25, 0xffff0000, v50
	v_pk_fma_f32 v[2:3], v[8:9], v[2:3], v[24:25]
	v_cvt_pk_bf16_f32 v65, v2, v3
	global_store_dword v[20:21], v65, off
	v_lshl_add_u64 v[20:21], v[20:21], 0, v[22:23]
	s_waitcnt vmcnt(32)
	v_lshlrev_b32_e32 v24, 16, v51
	v_and_b32_e32 v25, 0xffff0000, v51
	v_pk_fma_f32 v[2:3], v[8:9], v[2:3], v[24:25]
	v_cvt_pk_bf16_f32 v65, v2, v3
	global_store_dword v[20:21], v65, off
	v_lshl_add_u64 v[20:21], v[20:21], 0, v[22:23]
	s_waitcnt vmcnt(32)
	v_lshlrev_b32_e32 v24, 16, v52
	v_and_b32_e32 v25, 0xffff0000, v52
	v_pk_fma_f32 v[2:3], v[8:9], v[2:3], v[24:25]
	v_cvt_pk_bf16_f32 v65, v2, v3
	global_store_dword v[20:21], v65, off
	v_lshl_add_u64 v[20:21], v[20:21], 0, v[22:23]
	s_waitcnt vmcnt(32)
	v_lshlrev_b32_e32 v24, 16, v53
	v_and_b32_e32 v25, 0xffff0000, v53
	v_pk_fma_f32 v[2:3], v[8:9], v[2:3], v[24:25]
	v_cvt_pk_bf16_f32 v65, v2, v3
	global_store_dword v[20:21], v65, off
	v_lshl_add_u64 v[20:21], v[20:21], 0, v[22:23]
	s_waitcnt vmcnt(32)
	v_lshlrev_b32_e32 v24, 16, v54
	v_and_b32_e32 v25, 0xffff0000, v54
	v_pk_fma_f32 v[2:3], v[8:9], v[2:3], v[24:25]
	v_cvt_pk_bf16_f32 v65, v2, v3
	global_store_dword v[20:21], v65, off
	v_lshl_add_u64 v[20:21], v[20:21], 0, v[22:23]
	s_waitcnt vmcnt(32)
	v_lshlrev_b32_e32 v24, 16, v55
	v_and_b32_e32 v25, 0xffff0000, v55
	v_pk_fma_f32 v[2:3], v[8:9], v[2:3], v[24:25]
	v_cvt_pk_bf16_f32 v65, v2, v3
	global_store_dword v[20:21], v65, off
	v_lshl_add_u64 v[20:21], v[20:21], 0, v[22:23]
	s_waitcnt vmcnt(32)
	v_lshlrev_b32_e32 v24, 16, v56
	v_and_b32_e32 v25, 0xffff0000, v56
	v_pk_fma_f32 v[2:3], v[8:9], v[2:3], v[24:25]
	v_cvt_pk_bf16_f32 v65, v2, v3
	global_store_dword v[20:21], v65, off
	v_lshl_add_u64 v[20:21], v[20:21], 0, v[22:23]
	s_waitcnt vmcnt(32)
	v_lshlrev_b32_e32 v24, 16, v57
	v_and_b32_e32 v25, 0xffff0000, v57
	v_pk_fma_f32 v[2:3], v[8:9], v[2:3], v[24:25]
	v_cvt_pk_bf16_f32 v65, v2, v3
	global_store_dword v[20:21], v65, off
	v_lshl_add_u64 v[20:21], v[20:21], 0, v[22:23]
	s_waitcnt vmcnt(32)
	v_lshlrev_b32_e32 v24, 16, v58
	v_and_b32_e32 v25, 0xffff0000, v58
	v_pk_fma_f32 v[2:3], v[8:9], v[2:3], v[24:25]
	v_cvt_pk_bf16_f32 v65, v2, v3
	global_store_dword v[20:21], v65, off
	v_lshl_add_u64 v[20:21], v[20:21], 0, v[22:23]
	s_waitcnt vmcnt(32)
	v_lshlrev_b32_e32 v24, 16, v59
	v_and_b32_e32 v25, 0xffff0000, v59
	v_pk_fma_f32 v[2:3], v[8:9], v[2:3], v[24:25]
	v_cvt_pk_bf16_f32 v65, v2, v3
	global_store_dword v[20:21], v65, off
	v_lshl_add_u64 v[20:21], v[20:21], 0, v[22:23]
	s_waitcnt vmcnt(32)
	v_lshlrev_b32_e32 v24, 16, v60
	v_and_b32_e32 v25, 0xffff0000, v60
	v_pk_fma_f32 v[2:3], v[8:9], v[2:3], v[24:25]
	v_cvt_pk_bf16_f32 v65, v2, v3
	global_store_dword v[20:21], v65, off
	v_lshl_add_u64 v[20:21], v[20:21], 0, v[22:23]
	s_waitcnt vmcnt(32)
	v_lshlrev_b32_e32 v24, 16, v61
	v_and_b32_e32 v25, 0xffff0000, v61
	v_pk_fma_f32 v[2:3], v[8:9], v[2:3], v[24:25]
	v_cvt_pk_bf16_f32 v65, v2, v3
	global_store_dword v[20:21], v65, off
	v_lshl_add_u64 v[20:21], v[20:21], 0, v[22:23]
	s_waitcnt vmcnt(32)
	v_lshlrev_b32_e32 v24, 16, v62
	v_and_b32_e32 v25, 0xffff0000, v62
	v_pk_fma_f32 v[2:3], v[8:9], v[2:3], v[24:25]
	v_cvt_pk_bf16_f32 v65, v2, v3
	global_store_dword v[20:21], v65, off
	v_lshl_add_u64 v[20:21], v[20:21], 0, v[22:23]
	s_waitcnt vmcnt(32)
	v_lshlrev_b32_e32 v24, 16, v63
	v_and_b32_e32 v25, 0xffff0000, v63
	v_pk_fma_f32 v[2:3], v[8:9], v[2:3], v[24:25]
	v_cvt_pk_bf16_f32 v65, v2, v3
	global_store_dword v[20:21], v65, off
	v_lshl_add_u64 v[20:21], v[20:21], 0, v[22:23]
	s_waitcnt vmcnt(32)
	v_lshlrev_b32_e32 v24, 16, v64
	v_and_b32_e32 v25, 0xffff0000, v64
	v_pk_fma_f32 v[2:3], v[8:9], v[2:3], v[24:25]
	v_add_u32_e32 v26, s3, v26
	v_cmp_lt_i32_e32 vcc, s41, v26
	s_or_b64 s[10:11], vcc, s[10:11]
	s_andn2_b64 exec, exec, s[10:11]
	s_cbranch_execnz .LBB0_377
